# fused final norm: row sums polled in two halves (rows of blocks 0-3, then 4-7), second poll issued before the first half's stores so its wait overlaps them; gain loads issued before the poll
# speedup vs baseline: 1.0058x; 1.0058x over previous
.Lres_noaout:
	s_cmp_eq_u32 s12, 16
	s_cbranch_scc0 .Lres_noaout_old
	s_sub_u32 s0, s58, 0x20800
	s_subb_u32 s1, s59, 0
	v_lshl_add_u64 v[198:199], v[176:177], 3, s[0:1]
	s_mov_b32 s44, 0
	s_mov_b32 s45, 0x42700000
	global_load_dwordx4 v[230:233], v[246:247], off
	global_load_dwordx4 v[234:237], v[246:247], off offset:16
	global_load_dwordx4 v[238:241], v[246:247], off offset:128
	global_load_dwordx4 v[242:245], v[246:247], off offset:144
	s_mov_b64 s[42:43], 0x20000
	v_lshl_add_u64 v[180:181], v[246:247], 0, s[42:43]
	global_load_dwordx4 v[146:149], v[180:181], off
	global_load_dwordx4 v[150:153], v[180:181], off offset:16
	global_load_dwordx4 v[176:179], v[180:181], off offset:128
	global_load_dwordx4 v[202:205], v[180:181], off offset:144
	s_mov_b64 s[42:43], 0x40000
	v_lshl_add_u64 v[180:181], v[246:247], 0, s[42:43]
	global_load_dwordx4 v[182:185], v[180:181], off
	global_load_dwordx4 v[186:189], v[180:181], off offset:16
	global_load_dwordx4 v[190:193], v[180:181], off offset:128
	global_load_dwordx4 v[194:197], v[180:181], off offset:144
	s_waitcnt vmcnt(8)
	v_pk_fma_f32 v[126:127], v[126:127], v[142:143], v[230:231]
	v_pk_fma_f32 v[128:129], v[128:129], v[144:145], v[232:233]
	v_pk_fma_f32 v[122:123], v[122:123], v[138:139], v[234:235]
	v_pk_fma_f32 v[124:125], v[124:125], v[140:141], v[236:237]
	v_pk_fma_f32 v[118:119], v[118:119], v[134:135], v[238:239]
	v_pk_fma_f32 v[120:121], v[120:121], v[136:137], v[240:241]
	v_pk_fma_f32 v[114:115], v[114:115], v[130:131], v[242:243]
	v_pk_fma_f32 v[116:117], v[116:117], v[132:133], v[244:245]
	v_mul_f32_e32 v250, v126, v126
	v_mul_f32_e32 v251, v118, v118
	v_fmac_f32_e32 v250, v127, v127
	v_fmac_f32_e32 v251, v119, v119
	v_fmac_f32_e32 v250, v128, v128
	v_fmac_f32_e32 v251, v120, v120
	v_fmac_f32_e32 v250, v129, v129
	v_fmac_f32_e32 v251, v121, v121
	v_fmac_f32_e32 v250, v122, v122
	v_fmac_f32_e32 v251, v114, v114
	v_fmac_f32_e32 v250, v123, v123
	v_fmac_f32_e32 v251, v115, v115
	v_fmac_f32_e32 v250, v124, v124
	v_fmac_f32_e32 v251, v116, v116
	v_fmac_f32_e32 v250, v125, v125
	v_fmac_f32_e32 v251, v117, v117
	s_mov_b64 s[42:43], 0x60000
	v_lshl_add_u64 v[180:181], v[246:247], 0, s[42:43]
	global_load_dwordx4 v[230:233], v[180:181], off
	global_load_dwordx4 v[234:237], v[180:181], off offset:16
	global_load_dwordx4 v[238:241], v[180:181], off offset:128
	global_load_dwordx4 v[242:245], v[180:181], off offset:144
	v_add_f32_e32 v250, v250, v251
	ds_bpermute_b32 v251, v200, v250
	s_waitcnt lgkmcnt(0)
	v_add_f32_e32 v250, v250, v251
	ds_bpermute_b32 v251, v201, v250
	s_waitcnt lgkmcnt(0)
	v_add_f32_e32 v250, v250, v251
	v_cvt_f64_f32_e32 v[180:181], v250
	s_nop 0
	v_add_f64 v[180:181], v[180:181], s[44:45]
	s_and_saveexec_b64 s[42:43], s[38:39]
	global_atomic_add_f64 v[198:199], v[180:181], off
	s_mov_b64 exec, s[42:43]
	s_nop 1
	s_waitcnt vmcnt(9)
	v_pk_fma_f32 v[110:111], v[110:111], v[142:143], v[146:147]
	v_pk_fma_f32 v[112:113], v[112:113], v[144:145], v[148:149]
	v_pk_fma_f32 v[106:107], v[106:107], v[138:139], v[150:151]
	v_pk_fma_f32 v[108:109], v[108:109], v[140:141], v[152:153]
	v_pk_fma_f32 v[102:103], v[102:103], v[134:135], v[176:177]
	v_pk_fma_f32 v[104:105], v[104:105], v[136:137], v[178:179]
	v_pk_fma_f32 v[98:99], v[98:99], v[130:131], v[202:203]
	v_pk_fma_f32 v[100:101], v[100:101], v[132:133], v[204:205]
	v_mul_f32_e32 v250, v110, v110
	v_mul_f32_e32 v251, v102, v102
	v_fmac_f32_e32 v250, v111, v111
	v_fmac_f32_e32 v251, v103, v103
	v_fmac_f32_e32 v250, v112, v112
	v_fmac_f32_e32 v251, v104, v104
	v_fmac_f32_e32 v250, v113, v113
	v_fmac_f32_e32 v251, v105, v105
	v_fmac_f32_e32 v250, v106, v106
	v_fmac_f32_e32 v251, v98, v98
	v_fmac_f32_e32 v250, v107, v107
	v_fmac_f32_e32 v251, v99, v99
	v_fmac_f32_e32 v250, v108, v108
	v_fmac_f32_e32 v251, v100, v100
	v_fmac_f32_e32 v250, v109, v109
	v_fmac_f32_e32 v251, v101, v101
	s_mov_b64 s[42:43], 0x100000
	v_lshl_add_u64 v[180:181], v[246:247], 0, s[42:43]
	global_load_dwordx4 v[146:149], v[180:181], off
	global_load_dwordx4 v[150:153], v[180:181], off offset:16
	global_load_dwordx4 v[176:179], v[180:181], off offset:128
	global_load_dwordx4 v[202:205], v[180:181], off offset:144
	v_add_f32_e32 v250, v250, v251
	ds_bpermute_b32 v251, v200, v250
	s_waitcnt lgkmcnt(0)
	v_add_f32_e32 v250, v250, v251
	ds_bpermute_b32 v251, v201, v250
	s_waitcnt lgkmcnt(0)
	v_add_f32_e32 v250, v250, v251
	v_cvt_f64_f32_e32 v[180:181], v250
	s_nop 0
	v_add_f64 v[180:181], v[180:181], s[44:45]
	s_and_saveexec_b64 s[42:43], s[38:39]
	global_atomic_add_f64 v[198:199], v[180:181], off offset:128
	s_mov_b64 exec, s[42:43]
	s_nop 1
	s_waitcnt vmcnt(10)
	v_pk_fma_f32 v[94:95], v[94:95], v[142:143], v[182:183]
	v_pk_fma_f32 v[96:97], v[96:97], v[144:145], v[184:185]
	v_pk_fma_f32 v[90:91], v[90:91], v[138:139], v[186:187]
	v_pk_fma_f32 v[92:93], v[92:93], v[140:141], v[188:189]
	v_pk_fma_f32 v[86:87], v[86:87], v[134:135], v[190:191]
	v_pk_fma_f32 v[88:89], v[88:89], v[136:137], v[192:193]
	v_pk_fma_f32 v[82:83], v[82:83], v[130:131], v[194:195]
	v_pk_fma_f32 v[84:85], v[84:85], v[132:133], v[196:197]
	v_mul_f32_e32 v250, v94, v94
	v_mul_f32_e32 v251, v86, v86
	v_fmac_f32_e32 v250, v95, v95
	v_fmac_f32_e32 v251, v87, v87
	v_fmac_f32_e32 v250, v96, v96
	v_fmac_f32_e32 v251, v88, v88
	v_fmac_f32_e32 v250, v97, v97
	v_fmac_f32_e32 v251, v89, v89
	v_fmac_f32_e32 v250, v90, v90
	v_fmac_f32_e32 v251, v82, v82
	v_fmac_f32_e32 v250, v91, v91
	v_fmac_f32_e32 v251, v83, v83
	v_fmac_f32_e32 v250, v92, v92
	v_fmac_f32_e32 v251, v84, v84
	v_fmac_f32_e32 v250, v93, v93
	v_fmac_f32_e32 v251, v85, v85
	s_mov_b64 s[42:43], 0x120000
	v_lshl_add_u64 v[180:181], v[246:247], 0, s[42:43]
	global_load_dwordx4 v[182:185], v[180:181], off
	global_load_dwordx4 v[186:189], v[180:181], off offset:16
	global_load_dwordx4 v[190:193], v[180:181], off offset:128
	global_load_dwordx4 v[194:197], v[180:181], off offset:144
	v_add_f32_e32 v250, v250, v251
	ds_bpermute_b32 v251, v200, v250
	s_waitcnt lgkmcnt(0)
	v_add_f32_e32 v250, v250, v251
	ds_bpermute_b32 v251, v201, v250
	s_waitcnt lgkmcnt(0)
	v_add_f32_e32 v250, v250, v251
	v_cvt_f64_f32_e32 v[180:181], v250
	s_nop 0
	v_add_f64 v[180:181], v[180:181], s[44:45]
	s_and_saveexec_b64 s[42:43], s[38:39]
	global_atomic_add_f64 v[198:199], v[180:181], off offset:256
	s_mov_b64 exec, s[42:43]
	s_nop 1
	s_waitcnt vmcnt(11)
	v_pk_fma_f32 v[78:79], v[78:79], v[142:143], v[230:231]
	v_pk_fma_f32 v[80:81], v[80:81], v[144:145], v[232:233]
	v_pk_fma_f32 v[74:75], v[74:75], v[138:139], v[234:235]
	v_pk_fma_f32 v[76:77], v[76:77], v[140:141], v[236:237]
	v_pk_fma_f32 v[70:71], v[70:71], v[134:135], v[238:239]
	v_pk_fma_f32 v[72:73], v[72:73], v[136:137], v[240:241]
	v_pk_fma_f32 v[66:67], v[66:67], v[130:131], v[242:243]
	v_pk_fma_f32 v[68:69], v[68:69], v[132:133], v[244:245]
	v_mul_f32_e32 v250, v78, v78
	v_mul_f32_e32 v251, v70, v70
	v_fmac_f32_e32 v250, v79, v79
	v_fmac_f32_e32 v251, v71, v71
	v_fmac_f32_e32 v250, v80, v80
	v_fmac_f32_e32 v251, v72, v72
	v_fmac_f32_e32 v250, v81, v81
	v_fmac_f32_e32 v251, v73, v73
	v_fmac_f32_e32 v250, v74, v74
	v_fmac_f32_e32 v251, v66, v66
	v_fmac_f32_e32 v250, v75, v75
	v_fmac_f32_e32 v251, v67, v67
	v_fmac_f32_e32 v250, v76, v76
	v_fmac_f32_e32 v251, v68, v68
	v_fmac_f32_e32 v250, v77, v77
	v_fmac_f32_e32 v251, v69, v69
	s_mov_b64 s[42:43], 0x140000
	v_lshl_add_u64 v[180:181], v[246:247], 0, s[42:43]
	global_load_dwordx4 v[230:233], v[180:181], off
	global_load_dwordx4 v[234:237], v[180:181], off offset:16
	global_load_dwordx4 v[238:241], v[180:181], off offset:128
	global_load_dwordx4 v[242:245], v[180:181], off offset:144
	v_add_f32_e32 v250, v250, v251
	ds_bpermute_b32 v251, v200, v250
	s_waitcnt lgkmcnt(0)
	v_add_f32_e32 v250, v250, v251
	ds_bpermute_b32 v251, v201, v250
	s_waitcnt lgkmcnt(0)
	v_add_f32_e32 v250, v250, v251
	v_cvt_f64_f32_e32 v[180:181], v250
	s_nop 0
	v_add_f64 v[180:181], v[180:181], s[44:45]
	s_and_saveexec_b64 s[42:43], s[38:39]
	global_atomic_add_f64 v[198:199], v[180:181], off offset:384
	s_mov_b64 exec, s[42:43]
	s_nop 1
	s_waitcnt vmcnt(11)
	v_pk_fma_f32 v[62:63], v[62:63], v[142:143], v[146:147]
	v_pk_fma_f32 v[64:65], v[64:65], v[144:145], v[148:149]
	v_pk_fma_f32 v[58:59], v[58:59], v[138:139], v[150:151]
	v_pk_fma_f32 v[60:61], v[60:61], v[140:141], v[152:153]
	v_pk_fma_f32 v[54:55], v[54:55], v[134:135], v[176:177]
	v_pk_fma_f32 v[56:57], v[56:57], v[136:137], v[178:179]
	v_pk_fma_f32 v[50:51], v[50:51], v[130:131], v[202:203]
	v_pk_fma_f32 v[52:53], v[52:53], v[132:133], v[204:205]
	v_mul_f32_e32 v250, v62, v62
	v_mul_f32_e32 v251, v54, v54
	v_fmac_f32_e32 v250, v63, v63
	v_fmac_f32_e32 v251, v55, v55
	v_fmac_f32_e32 v250, v64, v64
	v_fmac_f32_e32 v251, v56, v56
	v_fmac_f32_e32 v250, v65, v65
	v_fmac_f32_e32 v251, v57, v57
	v_fmac_f32_e32 v250, v58, v58
	v_fmac_f32_e32 v251, v50, v50
	v_fmac_f32_e32 v250, v59, v59
	v_fmac_f32_e32 v251, v51, v51
	v_fmac_f32_e32 v250, v60, v60
	v_fmac_f32_e32 v251, v52, v52
	v_fmac_f32_e32 v250, v61, v61
	v_fmac_f32_e32 v251, v53, v53
	s_mov_b64 s[42:43], 0x160000
	v_lshl_add_u64 v[180:181], v[246:247], 0, s[42:43]
	global_load_dwordx4 v[146:149], v[180:181], off
	global_load_dwordx4 v[150:153], v[180:181], off offset:16
	global_load_dwordx4 v[176:179], v[180:181], off offset:128
	global_load_dwordx4 v[202:205], v[180:181], off offset:144
	v_add_f32_e32 v250, v250, v251
	ds_bpermute_b32 v251, v200, v250
	s_waitcnt lgkmcnt(0)
	v_add_f32_e32 v250, v250, v251
	ds_bpermute_b32 v251, v201, v250
	s_waitcnt lgkmcnt(0)
	v_add_f32_e32 v250, v250, v251
	v_cvt_f64_f32_e32 v[180:181], v250
	s_nop 0
	v_add_f64 v[180:181], v[180:181], s[44:45]
	s_and_saveexec_b64 s[42:43], s[38:39]
	global_atomic_add_f64 v[198:199], v[180:181], off offset:1024
	s_mov_b64 exec, s[42:43]
	s_nop 1
	s_waitcnt vmcnt(11)
	v_pk_fma_f32 v[46:47], v[46:47], v[142:143], v[182:183]
	v_pk_fma_f32 v[48:49], v[48:49], v[144:145], v[184:185]
	v_pk_fma_f32 v[42:43], v[42:43], v[138:139], v[186:187]
	v_pk_fma_f32 v[44:45], v[44:45], v[140:141], v[188:189]
	v_pk_fma_f32 v[38:39], v[38:39], v[134:135], v[190:191]
	v_pk_fma_f32 v[40:41], v[40:41], v[136:137], v[192:193]
	v_pk_fma_f32 v[34:35], v[34:35], v[130:131], v[194:195]
	v_pk_fma_f32 v[36:37], v[36:37], v[132:133], v[196:197]
	v_mul_f32_e32 v250, v46, v46
	v_mul_f32_e32 v251, v38, v38
	v_fmac_f32_e32 v250, v47, v47
	v_fmac_f32_e32 v251, v39, v39
	v_fmac_f32_e32 v250, v48, v48
	v_fmac_f32_e32 v251, v40, v40
	v_fmac_f32_e32 v250, v49, v49
	v_fmac_f32_e32 v251, v41, v41
	v_fmac_f32_e32 v250, v42, v42
	v_fmac_f32_e32 v251, v34, v34
	v_fmac_f32_e32 v250, v43, v43
	v_fmac_f32_e32 v251, v35, v35
	v_fmac_f32_e32 v250, v44, v44
	v_fmac_f32_e32 v251, v36, v36
	v_fmac_f32_e32 v250, v45, v45
	v_fmac_f32_e32 v251, v37, v37
	v_add_f32_e32 v250, v250, v251
	ds_bpermute_b32 v251, v200, v250
	s_waitcnt lgkmcnt(0)
	v_add_f32_e32 v250, v250, v251
	ds_bpermute_b32 v251, v201, v250
	s_waitcnt lgkmcnt(0)
	v_add_f32_e32 v250, v250, v251
	v_cvt_f64_f32_e32 v[180:181], v250
	s_nop 0
	v_add_f64 v[180:181], v[180:181], s[44:45]
	s_and_saveexec_b64 s[42:43], s[38:39]
	global_atomic_add_f64 v[198:199], v[180:181], off offset:1152
	s_mov_b64 exec, s[42:43]
	s_nop 1
	s_waitcnt vmcnt(7)
	v_pk_fma_f32 v[30:31], v[30:31], v[142:143], v[230:231]
	v_pk_fma_f32 v[32:33], v[32:33], v[144:145], v[232:233]
	v_pk_fma_f32 v[26:27], v[26:27], v[138:139], v[234:235]
	v_pk_fma_f32 v[28:29], v[28:29], v[140:141], v[236:237]
	v_pk_fma_f32 v[22:23], v[22:23], v[134:135], v[238:239]
	v_pk_fma_f32 v[24:25], v[24:25], v[136:137], v[240:241]
	v_pk_fma_f32 v[18:19], v[18:19], v[130:131], v[242:243]
	v_pk_fma_f32 v[20:21], v[20:21], v[132:133], v[244:245]
	v_mul_f32_e32 v250, v30, v30
	v_mul_f32_e32 v251, v22, v22
	v_fmac_f32_e32 v250, v31, v31
	v_fmac_f32_e32 v251, v23, v23
	v_fmac_f32_e32 v250, v32, v32
	v_fmac_f32_e32 v251, v24, v24
	v_fmac_f32_e32 v250, v33, v33
	v_fmac_f32_e32 v251, v25, v25
	v_fmac_f32_e32 v250, v26, v26
	v_fmac_f32_e32 v251, v18, v18
	v_fmac_f32_e32 v250, v27, v27
	v_fmac_f32_e32 v251, v19, v19
	v_fmac_f32_e32 v250, v28, v28
	v_fmac_f32_e32 v251, v20, v20
	v_fmac_f32_e32 v250, v29, v29
	v_fmac_f32_e32 v251, v21, v21
	v_add_f32_e32 v250, v250, v251
	ds_bpermute_b32 v251, v200, v250
	s_waitcnt lgkmcnt(0)
	v_add_f32_e32 v250, v250, v251
	ds_bpermute_b32 v251, v201, v250
	s_waitcnt lgkmcnt(0)
	v_add_f32_e32 v250, v250, v251
	v_cvt_f64_f32_e32 v[180:181], v250
	s_nop 0
	v_add_f64 v[180:181], v[180:181], s[44:45]
	s_and_saveexec_b64 s[42:43], s[38:39]
	global_atomic_add_f64 v[198:199], v[180:181], off offset:1280
	s_mov_b64 exec, s[42:43]
	s_nop 1
	s_waitcnt vmcnt(3)
	v_pk_fma_f32 v[14:15], v[14:15], v[142:143], v[146:147]
	v_pk_fma_f32 v[16:17], v[16:17], v[144:145], v[148:149]
	v_pk_fma_f32 v[10:11], v[10:11], v[138:139], v[150:151]
	v_pk_fma_f32 v[12:13], v[12:13], v[140:141], v[152:153]
	v_pk_fma_f32 v[6:7], v[6:7], v[134:135], v[176:177]
	v_pk_fma_f32 v[8:9], v[8:9], v[136:137], v[178:179]
	v_pk_fma_f32 v[2:3], v[2:3], v[130:131], v[202:203]
	v_pk_fma_f32 v[4:5], v[4:5], v[132:133], v[204:205]
	v_mul_f32_e32 v250, v14, v14
	v_mul_f32_e32 v251, v6, v6
	v_fmac_f32_e32 v250, v15, v15
	v_fmac_f32_e32 v251, v7, v7
	v_fmac_f32_e32 v250, v16, v16
	v_fmac_f32_e32 v251, v8, v8
	v_fmac_f32_e32 v250, v17, v17
	v_fmac_f32_e32 v251, v9, v9
	v_fmac_f32_e32 v250, v10, v10
	v_fmac_f32_e32 v251, v2, v2
	v_fmac_f32_e32 v250, v11, v11
	v_fmac_f32_e32 v251, v3, v3
	v_fmac_f32_e32 v250, v12, v12
	v_fmac_f32_e32 v251, v4, v4
	v_fmac_f32_e32 v250, v13, v13
	v_fmac_f32_e32 v251, v5, v5
	v_add_f32_e32 v250, v250, v251
	ds_bpermute_b32 v251, v200, v250
	s_waitcnt lgkmcnt(0)
	v_add_f32_e32 v250, v250, v251
	ds_bpermute_b32 v251, v201, v250
	s_waitcnt lgkmcnt(0)
	v_add_f32_e32 v250, v250, v251
	v_cvt_f64_f32_e32 v[180:181], v250
	s_nop 0
	v_add_f64 v[180:181], v[180:181], s[44:45]
	s_and_saveexec_b64 s[42:43], s[38:39]
	global_atomic_add_f64 v[198:199], v[180:181], off offset:1408
	s_mov_b64 exec, s[42:43]
	s_nop 1
	v_readlane_b32 s0, v253, 60
	v_readlane_b32 s1, v253, 61
	v_lshl_or_b32 v250, s76, 8, v228
	v_mov_b32_e32 v251, 0
	s_nop 2
	v_lshl_add_u64 v[250:251], v[250:251], 2, s[0:1]
	global_load_dwordx4 v[182:185], v[250:251], off
	global_load_dwordx4 v[186:189], v[250:251], off offset:16
	global_load_dwordx4 v[190:193], v[250:251], off offset:128
	global_load_dwordx4 v[194:197], v[250:251], off offset:144
	v_and_b32_e32 v0, 15, v154
	v_lshlrev_b32_e32 v0, 2, v0
	s_mov_b32 s0, 0
	s_mov_b32 s1, 0x42c00000
	s_mov_b32 s6, 0
.Lfn_spinA:
	s_and_saveexec_b64 s[44:45], s[38:39]
	global_load_dwordx2 v[230:231], v[198:199], off sc1
	global_load_dwordx2 v[232:233], v[198:199], off offset:128 sc1
	global_load_dwordx2 v[234:235], v[198:199], off offset:256 sc1
	global_load_dwordx2 v[236:237], v[198:199], off offset:384 sc1
	s_mov_b64 exec, s[44:45]
	s_waitcnt vmcnt(0)
	s_and_saveexec_b64 s[44:45], s[38:39]
	v_min_f64 v[250:251], v[230:231], v[232:233]
	v_min_f64 v[250:251], v[250:251], v[234:235]
	v_min_f64 v[250:251], v[250:251], v[236:237]
	s_nop 1
	v_cmp_gt_f64_e32 vcc, s[0:1], v[250:251]
	s_mov_b64 exec, s[44:45]
	s_cbranch_vccz .Lfn_goA
	s_add_i32 s6, s6, 1
	s_cmp_lt_u32 s6, 0x1000
	s_cbranch_scc0 .Lfn_goA
	s_sleep 1
	s_branch .Lfn_spinA
.Lfn_goA:
	s_and_saveexec_b64 s[44:45], s[38:39]
	global_load_dwordx2 v[238:239], v[198:199], off offset:1024 sc1
	global_load_dwordx2 v[240:241], v[198:199], off offset:1152 sc1
	global_load_dwordx2 v[242:243], v[198:199], off offset:1280 sc1
	global_load_dwordx2 v[244:245], v[198:199], off offset:1408 sc1
	s_mov_b64 exec, s[44:45]
	v_add_f64 v[230:231], v[230:231], -s[0:1]
	v_add_f64 v[232:233], v[232:233], -s[0:1]
	v_add_f64 v[234:235], v[234:235], -s[0:1]
	v_add_f64 v[236:237], v[236:237], -s[0:1]
	v_cvt_f32_f64_e32 v230, v[230:231]
	v_cvt_f32_f64_e32 v232, v[232:233]
	v_cvt_f32_f64_e32 v234, v[234:235]
	v_cvt_f32_f64_e32 v236, v[236:237]
	s_nop 1
	ds_bpermute_b32 v230, v0, v230
	ds_bpermute_b32 v232, v0, v232
	ds_bpermute_b32 v234, v0, v234
	ds_bpermute_b32 v236, v0, v236
	s_waitcnt lgkmcnt(0)
	v_fmamk_f32 v230, v230, 0x3a000000, v207
	s_nop 0
	v_rsq_f32_e32 v230, v230
	s_nop 0
	v_pk_mul_f32 v[126:127], v[126:127], v[230:231] op_sel_hi:[1,0]
	v_pk_mul_f32 v[126:127], v[182:183], v[126:127]
	v_pk_mul_f32 v[128:129], v[128:129], v[230:231] op_sel_hi:[1,0]
	v_pk_mul_f32 v[128:129], v[184:185], v[128:129]
	v_pk_mul_f32 v[122:123], v[122:123], v[230:231] op_sel_hi:[1,0]
	v_pk_mul_f32 v[122:123], v[186:187], v[122:123]
	v_pk_mul_f32 v[124:125], v[124:125], v[230:231] op_sel_hi:[1,0]
	v_pk_mul_f32 v[124:125], v[188:189], v[124:125]
	v_pk_mul_f32 v[118:119], v[118:119], v[230:231] op_sel_hi:[1,0]
	v_pk_mul_f32 v[118:119], v[190:191], v[118:119]
	v_pk_mul_f32 v[120:121], v[120:121], v[230:231] op_sel_hi:[1,0]
	v_pk_mul_f32 v[120:121], v[192:193], v[120:121]
	v_pk_mul_f32 v[114:115], v[114:115], v[230:231] op_sel_hi:[1,0]
	v_pk_mul_f32 v[114:115], v[194:195], v[114:115]
	v_pk_mul_f32 v[116:117], v[116:117], v[230:231] op_sel_hi:[1,0]
	v_pk_mul_f32 v[116:117], v[196:197], v[116:117]
	global_store_dwordx4 v[248:249], v[126:129], off
	global_store_dwordx4 v[248:249], v[122:125], off offset:16
	global_store_dwordx4 v[248:249], v[118:121], off offset:128
	global_store_dwordx4 v[248:249], v[114:117], off offset:144
	v_fmamk_f32 v232, v232, 0x3a000000, v207
	s_nop 0
	v_rsq_f32_e32 v232, v232
	s_nop 0
	v_pk_mul_f32 v[110:111], v[110:111], v[232:233] op_sel_hi:[1,0]
	v_pk_mul_f32 v[110:111], v[182:183], v[110:111]
	v_pk_mul_f32 v[112:113], v[112:113], v[232:233] op_sel_hi:[1,0]
	v_pk_mul_f32 v[112:113], v[184:185], v[112:113]
	v_pk_mul_f32 v[106:107], v[106:107], v[232:233] op_sel_hi:[1,0]
	v_pk_mul_f32 v[106:107], v[186:187], v[106:107]
	v_pk_mul_f32 v[108:109], v[108:109], v[232:233] op_sel_hi:[1,0]
	v_pk_mul_f32 v[108:109], v[188:189], v[108:109]
	v_pk_mul_f32 v[102:103], v[102:103], v[232:233] op_sel_hi:[1,0]
	v_pk_mul_f32 v[102:103], v[190:191], v[102:103]
	v_pk_mul_f32 v[104:105], v[104:105], v[232:233] op_sel_hi:[1,0]
	v_pk_mul_f32 v[104:105], v[192:193], v[104:105]
	v_pk_mul_f32 v[98:99], v[98:99], v[232:233] op_sel_hi:[1,0]
	v_pk_mul_f32 v[98:99], v[194:195], v[98:99]
	v_pk_mul_f32 v[100:101], v[100:101], v[232:233] op_sel_hi:[1,0]
	v_pk_mul_f32 v[100:101], v[196:197], v[100:101]
	s_mov_b64 s[42:43], 0x20000
	v_lshl_add_u64 v[180:181], v[248:249], 0, s[42:43]
	global_store_dwordx4 v[180:181], v[110:113], off
	global_store_dwordx4 v[180:181], v[106:109], off offset:16
	global_store_dwordx4 v[180:181], v[102:105], off offset:128
	global_store_dwordx4 v[180:181], v[98:101], off offset:144
	v_fmamk_f32 v234, v234, 0x3a000000, v207
	s_nop 0
	v_rsq_f32_e32 v234, v234
	s_nop 0
	v_pk_mul_f32 v[94:95], v[94:95], v[234:235] op_sel_hi:[1,0]
	v_pk_mul_f32 v[94:95], v[182:183], v[94:95]
	v_pk_mul_f32 v[96:97], v[96:97], v[234:235] op_sel_hi:[1,0]
	v_pk_mul_f32 v[96:97], v[184:185], v[96:97]
	v_pk_mul_f32 v[90:91], v[90:91], v[234:235] op_sel_hi:[1,0]
	v_pk_mul_f32 v[90:91], v[186:187], v[90:91]
	v_pk_mul_f32 v[92:93], v[92:93], v[234:235] op_sel_hi:[1,0]
	v_pk_mul_f32 v[92:93], v[188:189], v[92:93]
	v_pk_mul_f32 v[86:87], v[86:87], v[234:235] op_sel_hi:[1,0]
	v_pk_mul_f32 v[86:87], v[190:191], v[86:87]
	v_pk_mul_f32 v[88:89], v[88:89], v[234:235] op_sel_hi:[1,0]
	v_pk_mul_f32 v[88:89], v[192:193], v[88:89]
	v_pk_mul_f32 v[82:83], v[82:83], v[234:235] op_sel_hi:[1,0]
	v_pk_mul_f32 v[82:83], v[194:195], v[82:83]
	v_pk_mul_f32 v[84:85], v[84:85], v[234:235] op_sel_hi:[1,0]
	v_pk_mul_f32 v[84:85], v[196:197], v[84:85]
	s_mov_b64 s[42:43], 0x40000
	v_lshl_add_u64 v[180:181], v[248:249], 0, s[42:43]
	global_store_dwordx4 v[180:181], v[94:97], off
	global_store_dwordx4 v[180:181], v[90:93], off offset:16
	global_store_dwordx4 v[180:181], v[86:89], off offset:128
	global_store_dwordx4 v[180:181], v[82:85], off offset:144
	v_fmamk_f32 v236, v236, 0x3a000000, v207
	s_nop 0
	v_rsq_f32_e32 v236, v236
	s_nop 0
	v_pk_mul_f32 v[78:79], v[78:79], v[236:237] op_sel_hi:[1,0]
	v_pk_mul_f32 v[78:79], v[182:183], v[78:79]
	v_pk_mul_f32 v[80:81], v[80:81], v[236:237] op_sel_hi:[1,0]
	v_pk_mul_f32 v[80:81], v[184:185], v[80:81]
	v_pk_mul_f32 v[74:75], v[74:75], v[236:237] op_sel_hi:[1,0]
	v_pk_mul_f32 v[74:75], v[186:187], v[74:75]
	v_pk_mul_f32 v[76:77], v[76:77], v[236:237] op_sel_hi:[1,0]
	v_pk_mul_f32 v[76:77], v[188:189], v[76:77]
	v_pk_mul_f32 v[70:71], v[70:71], v[236:237] op_sel_hi:[1,0]
	v_pk_mul_f32 v[70:71], v[190:191], v[70:71]
	v_pk_mul_f32 v[72:73], v[72:73], v[236:237] op_sel_hi:[1,0]
	v_pk_mul_f32 v[72:73], v[192:193], v[72:73]
	v_pk_mul_f32 v[66:67], v[66:67], v[236:237] op_sel_hi:[1,0]
	v_pk_mul_f32 v[66:67], v[194:195], v[66:67]
	v_pk_mul_f32 v[68:69], v[68:69], v[236:237] op_sel_hi:[1,0]
	v_pk_mul_f32 v[68:69], v[196:197], v[68:69]
	s_mov_b64 s[42:43], 0x60000
	v_lshl_add_u64 v[180:181], v[248:249], 0, s[42:43]
	global_store_dwordx4 v[180:181], v[78:81], off
	global_store_dwordx4 v[180:181], v[74:77], off offset:16
	global_store_dwordx4 v[180:181], v[70:73], off offset:128
	global_store_dwordx4 v[180:181], v[66:69], off offset:144
	s_waitcnt vmcnt(16)
	s_and_saveexec_b64 s[44:45], s[38:39]
	v_min_f64 v[250:251], v[238:239], v[240:241]
	v_min_f64 v[250:251], v[250:251], v[242:243]
	v_min_f64 v[250:251], v[250:251], v[244:245]
	s_nop 1
	v_cmp_gt_f64_e32 vcc, s[0:1], v[250:251]
	s_mov_b64 exec, s[44:45]
	s_cbranch_vccz .Lfn_goB
.Lfn_spinB:
	s_add_i32 s6, s6, 1
	s_cmp_lt_u32 s6, 0x1000
	s_cbranch_scc0 .Lfn_goB
	s_sleep 1
	s_and_saveexec_b64 s[44:45], s[38:39]
	global_load_dwordx2 v[238:239], v[198:199], off offset:1024 sc1
	global_load_dwordx2 v[240:241], v[198:199], off offset:1152 sc1
	global_load_dwordx2 v[242:243], v[198:199], off offset:1280 sc1
	global_load_dwordx2 v[244:245], v[198:199], off offset:1408 sc1
	s_mov_b64 exec, s[44:45]
	s_waitcnt vmcnt(0)
	s_and_saveexec_b64 s[44:45], s[38:39]
	v_min_f64 v[250:251], v[238:239], v[240:241]
	v_min_f64 v[250:251], v[250:251], v[242:243]
	v_min_f64 v[250:251], v[250:251], v[244:245]
	s_nop 1
	v_cmp_gt_f64_e32 vcc, s[0:1], v[250:251]
	s_mov_b64 exec, s[44:45]
	s_cbranch_vccz .Lfn_goB
	s_branch .Lfn_spinB
.Lfn_goB:
	v_add_f64 v[238:239], v[238:239], -s[0:1]
	v_add_f64 v[240:241], v[240:241], -s[0:1]
	v_add_f64 v[242:243], v[242:243], -s[0:1]
	v_add_f64 v[244:245], v[244:245], -s[0:1]
	v_cvt_f32_f64_e32 v238, v[238:239]
	v_cvt_f32_f64_e32 v240, v[240:241]
	v_cvt_f32_f64_e32 v242, v[242:243]
	v_cvt_f32_f64_e32 v244, v[244:245]
	s_nop 1
	ds_bpermute_b32 v238, v0, v238
	ds_bpermute_b32 v240, v0, v240
	ds_bpermute_b32 v242, v0, v242
	ds_bpermute_b32 v244, v0, v244
	s_waitcnt lgkmcnt(0)
	v_fmamk_f32 v238, v238, 0x3a000000, v207
	s_nop 0
	v_rsq_f32_e32 v238, v238
	s_nop 0
	v_pk_mul_f32 v[62:63], v[62:63], v[238:239] op_sel_hi:[1,0]
	v_pk_mul_f32 v[62:63], v[182:183], v[62:63]
	v_pk_mul_f32 v[64:65], v[64:65], v[238:239] op_sel_hi:[1,0]
	v_pk_mul_f32 v[64:65], v[184:185], v[64:65]
	v_pk_mul_f32 v[58:59], v[58:59], v[238:239] op_sel_hi:[1,0]
	v_pk_mul_f32 v[58:59], v[186:187], v[58:59]
	v_pk_mul_f32 v[60:61], v[60:61], v[238:239] op_sel_hi:[1,0]
	v_pk_mul_f32 v[60:61], v[188:189], v[60:61]
	v_pk_mul_f32 v[54:55], v[54:55], v[238:239] op_sel_hi:[1,0]
	v_pk_mul_f32 v[54:55], v[190:191], v[54:55]
	v_pk_mul_f32 v[56:57], v[56:57], v[238:239] op_sel_hi:[1,0]
	v_pk_mul_f32 v[56:57], v[192:193], v[56:57]
	v_pk_mul_f32 v[50:51], v[50:51], v[238:239] op_sel_hi:[1,0]
	v_pk_mul_f32 v[50:51], v[194:195], v[50:51]
	v_pk_mul_f32 v[52:53], v[52:53], v[238:239] op_sel_hi:[1,0]
	v_pk_mul_f32 v[52:53], v[196:197], v[52:53]
	s_mov_b64 s[42:43], 0x100000
	v_lshl_add_u64 v[180:181], v[248:249], 0, s[42:43]
	global_store_dwordx4 v[180:181], v[62:65], off
	global_store_dwordx4 v[180:181], v[58:61], off offset:16
	global_store_dwordx4 v[180:181], v[54:57], off offset:128
	global_store_dwordx4 v[180:181], v[50:53], off offset:144
	v_fmamk_f32 v240, v240, 0x3a000000, v207
	s_nop 0
	v_rsq_f32_e32 v240, v240
	s_nop 0
	v_pk_mul_f32 v[46:47], v[46:47], v[240:241] op_sel_hi:[1,0]
	v_pk_mul_f32 v[46:47], v[182:183], v[46:47]
	v_pk_mul_f32 v[48:49], v[48:49], v[240:241] op_sel_hi:[1,0]
	v_pk_mul_f32 v[48:49], v[184:185], v[48:49]
	v_pk_mul_f32 v[42:43], v[42:43], v[240:241] op_sel_hi:[1,0]
	v_pk_mul_f32 v[42:43], v[186:187], v[42:43]
	v_pk_mul_f32 v[44:45], v[44:45], v[240:241] op_sel_hi:[1,0]
	v_pk_mul_f32 v[44:45], v[188:189], v[44:45]
	v_pk_mul_f32 v[38:39], v[38:39], v[240:241] op_sel_hi:[1,0]
	v_pk_mul_f32 v[38:39], v[190:191], v[38:39]
	v_pk_mul_f32 v[40:41], v[40:41], v[240:241] op_sel_hi:[1,0]
	v_pk_mul_f32 v[40:41], v[192:193], v[40:41]
	v_pk_mul_f32 v[34:35], v[34:35], v[240:241] op_sel_hi:[1,0]
	v_pk_mul_f32 v[34:35], v[194:195], v[34:35]
	v_pk_mul_f32 v[36:37], v[36:37], v[240:241] op_sel_hi:[1,0]
	v_pk_mul_f32 v[36:37], v[196:197], v[36:37]
	s_mov_b64 s[42:43], 0x120000
	v_lshl_add_u64 v[180:181], v[248:249], 0, s[42:43]
	global_store_dwordx4 v[180:181], v[46:49], off
	global_store_dwordx4 v[180:181], v[42:45], off offset:16
	global_store_dwordx4 v[180:181], v[38:41], off offset:128
	global_store_dwordx4 v[180:181], v[34:37], off offset:144
	v_fmamk_f32 v242, v242, 0x3a000000, v207
	s_nop 0
	v_rsq_f32_e32 v242, v242
	s_nop 0
	v_pk_mul_f32 v[30:31], v[30:31], v[242:243] op_sel_hi:[1,0]
	v_pk_mul_f32 v[30:31], v[182:183], v[30:31]
	v_pk_mul_f32 v[32:33], v[32:33], v[242:243] op_sel_hi:[1,0]
	v_pk_mul_f32 v[32:33], v[184:185], v[32:33]
	v_pk_mul_f32 v[26:27], v[26:27], v[242:243] op_sel_hi:[1,0]
	v_pk_mul_f32 v[26:27], v[186:187], v[26:27]
	v_pk_mul_f32 v[28:29], v[28:29], v[242:243] op_sel_hi:[1,0]
	v_pk_mul_f32 v[28:29], v[188:189], v[28:29]
	v_pk_mul_f32 v[22:23], v[22:23], v[242:243] op_sel_hi:[1,0]
	v_pk_mul_f32 v[22:23], v[190:191], v[22:23]
	v_pk_mul_f32 v[24:25], v[24:25], v[242:243] op_sel_hi:[1,0]
	v_pk_mul_f32 v[24:25], v[192:193], v[24:25]
	v_pk_mul_f32 v[18:19], v[18:19], v[242:243] op_sel_hi:[1,0]
	v_pk_mul_f32 v[18:19], v[194:195], v[18:19]
	v_pk_mul_f32 v[20:21], v[20:21], v[242:243] op_sel_hi:[1,0]
	v_pk_mul_f32 v[20:21], v[196:197], v[20:21]
	s_mov_b64 s[42:43], 0x140000
	v_lshl_add_u64 v[180:181], v[248:249], 0, s[42:43]
	global_store_dwordx4 v[180:181], v[30:33], off
	global_store_dwordx4 v[180:181], v[26:29], off offset:16
	global_store_dwordx4 v[180:181], v[22:25], off offset:128
	global_store_dwordx4 v[180:181], v[18:21], off offset:144
	v_fmamk_f32 v244, v244, 0x3a000000, v207
	s_nop 0
	v_rsq_f32_e32 v244, v244
	s_nop 0
	v_pk_mul_f32 v[14:15], v[14:15], v[244:245] op_sel_hi:[1,0]
	v_pk_mul_f32 v[14:15], v[182:183], v[14:15]
	v_pk_mul_f32 v[16:17], v[16:17], v[244:245] op_sel_hi:[1,0]
	v_pk_mul_f32 v[16:17], v[184:185], v[16:17]
	v_pk_mul_f32 v[10:11], v[10:11], v[244:245] op_sel_hi:[1,0]
	v_pk_mul_f32 v[10:11], v[186:187], v[10:11]
	v_pk_mul_f32 v[12:13], v[12:13], v[244:245] op_sel_hi:[1,0]
	v_pk_mul_f32 v[12:13], v[188:189], v[12:13]
	v_pk_mul_f32 v[6:7], v[6:7], v[244:245] op_sel_hi:[1,0]
	v_pk_mul_f32 v[6:7], v[190:191], v[6:7]
	v_pk_mul_f32 v[8:9], v[8:9], v[244:245] op_sel_hi:[1,0]
	v_pk_mul_f32 v[8:9], v[192:193], v[8:9]
	v_pk_mul_f32 v[2:3], v[2:3], v[244:245] op_sel_hi:[1,0]
	v_pk_mul_f32 v[2:3], v[194:195], v[2:3]
	v_pk_mul_f32 v[4:5], v[4:5], v[244:245] op_sel_hi:[1,0]
	v_pk_mul_f32 v[4:5], v[196:197], v[4:5]
	s_mov_b64 s[42:43], 0x160000
	v_lshl_add_u64 v[180:181], v[248:249], 0, s[42:43]
	global_store_dwordx4 v[180:181], v[14:17], off
	global_store_dwordx4 v[180:181], v[10:13], off offset:16
	global_store_dwordx4 v[180:181], v[6:9], off offset:128
	global_store_dwordx4 v[180:181], v[2:5], off offset:144
	s_branch .LBB0_487
